# P1->P2 barrier scoped to the XCD pair that owns a batch (64 workgroups, wbl2+inv) plus a one-time 8 us start stagger between the four pairs so store bursts do not coincide
# baseline (speedup 1.0000x reference)
; #define LAS __attribute__((address_space(3)))
; __global__ void __launch_bounds__(NWAVES * 64, 2) mk_fwd(Args a) {
;     ...
;     for (int l = 0; l < NLAYER; ++l) {
;         unsigned char* wl = ws + WS_W + (size_t)l * W_LAYER;
; #pragma unroll 1
;         for (int rep1 = 0; rep1 < REP_P1; ++rep1) {
;             pg8::Gemm g{XB, (const bf16u*)(wl + WL_IN), NTOK, INW, DMOD}; int bxp = bx; asm volatile("" : "+s"(bxp)); pg8::StaticOrder S; S.init(NTOK, INW, G, bxp);
;             pg8::Unit u0; int pm0 = -1; if (S.next(0, u0)) pm0 = u0.pm;
;             { int tt_ = threadIdx.x; asm volatile("" : "+v"(tt_)); if (pm0 >= 0 && tt_ < 256) ((LAS float*)(L + RING_BYTES))[tt_] = pg8::row_rstd(ssqA, pm0 * 256 + tt_); }
;             __syncthreads();
;             pg8::EpiProj E{Qb, BUFE, ssqA, rope, attn_body::C2, pm0, (const LAS float*)(L + RING_BYTES)};
;             pg8::gemm_phase<pg8::EpiProj, pg8::StaticOrder, true, true>(L, g, S, E);
;     ...
;                 const int nwg5 = (NTOK / 256) * (2 * DFF / 256), rem = nwg5 % G;
;                 const bool light = (rem == 0) || (bxp >= rem);
;                 if (light) { int tc_ = threadIdx.x; asm volatile("" : "+v"(tc_)); const int lnc = tc_ & 63; const int nl = (rem == 0) ? G : G - rem, li = (rem == 0) ? bxp : bxp - rem;
.LBB0_135:
	v_writelane_b32 v255, s72, 2
	s_nop 1
	v_writelane_b32 v255, s73, 3
	s_or_b64 exec, exec, s[2:3]
	s_add_u32 s0, s42, 0x100000
	s_addc_u32 s1, s43, 0
	v_writelane_b32 v255, s0, 4
	v_readlane_b32 s4, v253, 38
	s_mov_b32 s91, 0
	v_writelane_b32 v255, s1, 5
	s_add_u32 s0, s42, 0x200000
	s_addc_u32 s1, s43, 0
	s_add_u32 s82, s42, 0x9e00000
	s_addc_u32 s83, s43, 0
	s_add_u32 s6, s42, 0xbe00000
	v_writelane_b32 v255, s0, 6
	s_addc_u32 s7, s43, 0
	v_mov_b32_e32 v245, 0x358637bd
	v_writelane_b32 v255, s1, 7
	s_add_u32 s0, s42, 0xde00000
	v_writelane_b32 v255, s0, 8
	s_addc_u32 s0, s43, 0
	v_writelane_b32 v255, s0, 9
	s_add_u32 s0, s42, 0xfe00000
	v_writelane_b32 v255, s0, 10
	s_addc_u32 s0, s43, 0
	s_add_u32 s28, s42, 0x11e00000
	s_addc_u32 s29, s43, 0
	s_add_u32 s30, s42, 0x13e00000
	s_addc_u32 s31, s43, 0
	v_writelane_b32 v255, s0, 11
	s_add_u32 s0, s42, 0x17e00000
	s_addc_u32 s1, s43, 0
	v_writelane_b32 v255, s0, 12
	s_movk_i32 s61, 0x2000
	v_mov_b32_e32 v1, 0
	v_writelane_b32 v255, s1, 13
	s_add_u32 s0, s42, 0x19e00000
	s_addc_u32 s1, s43, 0
	s_add_u32 s14, s42, 0x1be00000
	s_addc_u32 s15, s43, 0
	s_add_u32 s86, s42, 0x1de00000
	s_addc_u32 s87, s43, 0
	s_ashr_i32 s79, s80, 31
	v_writelane_b32 v255, s0, 14
	s_cmpk_eq_i32 s80, 0x100
	s_mov_b32 s88, 0x8000
	v_writelane_b32 v255, s1, 15
	s_cselect_b64 s[0:1], -1, 0
	v_writelane_b32 v255, s0, 16
	s_lshl_b32 s89, s80, 2
	s_mov_b32 s27, 0xa000
	v_writelane_b32 v255, s1, 17
	s_abs_i32 s0, s80
	s_waitcnt lgkmcnt(0)
	v_cvt_f32_u32_e32 v0, s0
	s_lshl_b32 s1, s4, 5
	v_writelane_b32 v255, s1, 18
	s_sub_i32 s1, 0, s0
	v_rcp_iflag_f32_e32 v0, v0
	s_mov_b32 s26, 0xc000
	v_mov_b32_e32 v234, 1
	s_movk_i32 s10, 0x3ff
	v_mul_f32_e32 v0, 0x4f7ffffe, v0
	v_cvt_u32_f32_e32 v0, v0
	v_mov_b64_e32 v[236:237], 0x800
	v_mov_b32_e32 v235, 0x3e38aa3b
	v_mov_b32_e32 v248, 0xff800000
	v_readfirstlane_b32 s2, v0
	s_mul_i32 s1, s1, s2
	s_mul_hi_u32 s1, s2, s1
	s_add_i32 s2, s2, s1
	s_mul_hi_u32 s1, s2, 0x580
	s_mul_i32 s1, s1, s0
	s_sub_i32 s1, 0x580, s1
	s_sub_i32 s2, s1, s0
	s_cmp_ge_u32 s1, s0
	s_cselect_b32 s1, s2, s1
	s_sub_i32 s2, s1, s0
	s_cmp_ge_u32 s1, s0
	s_cselect_b32 s5, s2, s1
	s_cmp_eq_u32 s5, 0
	s_cselect_b64 s[2:3], -1, 0
	s_sub_i32 s0, s80, s5
	s_lshl_b32 s0, s0, 3
	v_writelane_b32 v255, s0, 19
	s_lshl_b32 s0, s80, 4
	v_writelane_b32 v255, s0, 20
	s_lshl_b32 s0, s4, 6
	s_lshl_b32 s1, s5, 9
	s_sub_i32 s8, s0, s1
	s_sub_i32 s0, s34, s1
	v_writelane_b32 v255, s0, 21
	s_lshl_b32 s0, s4, 2
	s_lshl_b32 s1, s5, 5
	s_sub_i32 s0, s0, s1
	v_writelane_b32 v255, s0, 22
	s_lshl_b32 s0, s80, 5
	s_sub_i32 s0, s0, s1
	v_writelane_b32 v255, s0, 23
	s_lshl_b32 s0, s4, 7
	s_lshl_b32 s1, s5, 10
	s_sub_i32 s0, s0, s1
	s_add_i32 s0, s0, 0xfff92000
	v_writelane_b32 v255, s0, 24
	s_lshl_b32 s0, s80, 10
	s_sub_i32 s0, s0, s1
	v_writelane_b32 v255, s0, 25
	s_lshl_b32 s0, s5, 3
	s_sub_i32 s1, s4, s0
	s_add_i32 s4, s1, 0xfffff240
	v_writelane_b32 v255, s4, 26
	s_mov_b32 s4, s74
	v_writelane_b32 v255, s4, 27
	s_sub_i32 s0, s74, s0
	s_xor_b64 s[2:3], s[2:3], -1
	v_writelane_b32 v255, s5, 28
	v_writelane_b32 v255, s0, 29
	s_add_i32 s0, s8, 0xfffc9000
	v_writelane_b32 v255, s0, 30
	s_add_i32 s0, s1, 0xfffff500
	v_writelane_b32 v255, s0, 31
	s_add_i32 s0, s1, 0xf500
	v_writelane_b32 v255, s0, 32
	v_writelane_b32 v255, s8, 33
	s_add_i32 s0, s8, 0xfffd4000
	v_writelane_b32 v255, s0, 34
	s_lshl_b32 s0, s80, 12
	s_lshl_b32 s1, s5, 12
	v_writelane_b32 v255, s5, 35
	s_sub_i32 s0, s0, s1
	v_writelane_b32 v255, s0, 36
	s_add_i32 s1, 0, 0x23fc0
	v_writelane_b32 v255, s1, 37
	s_add_i32 s1, 0, 0x23fc4
	v_writelane_b32 v255, s1, 38
	v_writelane_b32 v255, s2, 39
	s_lshl_b32 s44, s80, 6
	s_mov_b32 s5, 0x18000
	v_writelane_b32 v255, s3, 40
	v_writelane_b32 v255, s78, 41
	v_writelane_b32 v255, s82, 42
	s_mov_b32 s0, 0x50000
	v_mov_b64_e32 v[230:231], 0xff
	v_writelane_b32 v255, s83, 43
	s_mov_b32 s11, 0x41000000
	s_mov_b64 s[8:9], 0x40000
	s_mov_b64 s[70:71], 0x80
	s_mov_b64 s[62:63], 0x2000
	s_mov_b64 s[94:95], 0x20000
	s_mov_b64 s[72:73], 0x60000
	s_mov_b64 s[74:75], 0x80000
	s_mov_b64 s[66:67], 0xfe40000
	s_mov_b64 s[84:85], 0xfe40080
	s_mov_b32 s92, s91
	v_writelane_b32 v255, s79, 44
	s_barrier
	s_mov_b32 s98, 0
	s_mov_b32 s99, 0
	s_mov_b32 s100, 0
	s_cmpk_lg_i32 s80, 0x100
	s_cbranch_scc1 .Lgb_setup_done
	s_add_u32 s12, s42, 0x318000
	s_addc_u32 s13, s43, 0
	v_and_b32_e32 v2, 63, v244
	v_lshlrev_b32_e32 v3, 4, v2
	global_load_dwordx4 v[4:7], v3, s[12:13] sc1
	v_and_b32_e32 v8, 1, v2
	s_waitcnt vmcnt(0)
	v_readlane_b32 s1, v4, 0
	v_readlane_b32 s2, v5, 0
	v_readlane_b32 s3, v6, 0
	v_readlane_b32 s4, v7, 0
	v_readlane_b32 s16, v4, 1
	v_readlane_b32 s17, v5, 1
	v_readlane_b32 s18, v6, 1
	v_readlane_b32 s19, v7, 1
	v_cmp_eq_u32_e32 vcc, 1, v8
	s_nop 3
	v_mov_b32_e32 v9, s1
	v_mov_b32_e32 v10, s16
	v_cndmask_b32_e32 v9, v9, v10, vcc
	v_mov_b32_e32 v11, s2
	v_mov_b32_e32 v10, s17
	v_cndmask_b32_e32 v11, v11, v10, vcc
	v_mov_b32_e32 v12, s3
	v_mov_b32_e32 v10, s18
	v_cndmask_b32_e32 v12, v12, v10, vcc
	v_mov_b32_e32 v13, s4
	v_mov_b32_e32 v10, s19
	v_cndmask_b32_e32 v13, v13, v10, vcc
	v_xor_b32_e32 v9, v9, v4
	v_xor_b32_e32 v11, v11, v5
	v_xor_b32_e32 v12, v12, v6
	v_xor_b32_e32 v13, v13, v7
	v_or3_b32 v9, v9, v11, v12
	v_or_b32_e32 v9, v9, v13
	v_min_u32_e32 v10, v4, v5
	v_min3_u32 v10, v10, v6, v7
	v_cmp_ne_u32_e32 vcc, 0, v9
	v_cmp_eq_u32_e64 s[2:3], 0, v10
	s_nop 1
	s_or_b64 s[2:3], s[2:3], vcc
	s_cmp_lg_u64 s[2:3], 0
	s_cbranch_scc1 .Lgb_setup_done
	s_mov_b32 s98, 1
	v_readlane_b32 s4, v253, 1
	s_nop 3
	s_bfe_u32 s4, s4, 0x20001
	s_mul_i32 s4, s4, 2
	s_cmp_eq_u32 s4, 0
	s_cbranch_scc1 .Lgb_setup_done
.Lgb_stg_loop:
	s_sleep 127
	s_sub_u32 s4, s4, 1
	s_cmp_lg_u32 s4, 0
	s_cbranch_scc1 .Lgb_stg_loop

; __device__ __forceinline__ unsigned xb_ld(unsigned* p)              { return __hip_atomic_load(p, __ATOMIC_RELAXED, __HIP_MEMORY_SCOPE_AGENT); }
; __device__ __forceinline__ unsigned xb_add(unsigned* p, unsigned v) { return __hip_atomic_fetch_add(p, v, __ATOMIC_RELAXED, __HIP_MEMORY_SCOPE_AGENT); }
; #define XB_SPIN(cond, bar) do { unsigned _sp = 0; while (cond) { __builtin_amdgcn_s_sleep(1); \
;     if ((++_sp & 255u) == 0u) { if (xb_ld(&(bar)[XB_TMO])) break; if (_sp > XB_SPIN_CAP) { atomicAdd(&(bar)[XB_TMO], 1u); break; } } } } while (0)
; __device__ __forceinline__ void xcd_barrier(const XcdBarrier& b) {
;     asm volatile("s_waitcnt vmcnt(0)" ::: "memory");
;     __syncthreads();
;     if (threadIdx.x == 0) {
;         unsigned* bar = b.bar;
;         __builtin_amdgcn_s_waitcnt(0);
;         unsigned nloc = b.st[0], nx = b.st[1];
;         if (nloc == 0u) { xcd_barrier_complete(bar, b.x, nloc, nx); b.st[0] = nloc; b.st[1] = nx; }
;         const unsigned old = xb_add(&bar[XB_XSUB(b.x)], 1u);
;         const unsigned gen = old / nloc;
;         if (old + 1u == (gen + 1u) * nloc) {
;             __builtin_amdgcn_fence(__ATOMIC_RELEASE, "agent");
;             asm volatile("s_waitcnt vmcnt(0)" ::: "memory");
;             const unsigned og = xb_add(&bar[XB_TOP], 1u);
;             const unsigned tg = og / nx;
;             if (og + 1u == (tg + 1u) * nx) xb_add(&bar[XB_TOPGEN], 1u);
;             else XB_SPIN(xb_ld(&bar[XB_TOPGEN]) == tg, bar);
;             __builtin_amdgcn_fence(__ATOMIC_ACQUIRE, "agent");
;             xb_add(&bar[XB_XGEN(b.x)], 1u);
;             asm volatile("s_waitcnt vmcnt(0)" ::: "memory");
;         } else {
;             XB_SPIN(xb_ld(&bar[XB_XGEN(b.x)]) == gen, bar);
;             __builtin_amdgcn_fence(__ATOMIC_ACQUIRE, "agent");
;             asm volatile("s_waitcnt vmcnt(0)" ::: "memory");
;         }
;     }
;     __syncthreads();
; }
.LBB0_192:
	s_waitcnt vmcnt(0)
	s_waitcnt vmcnt(0) lgkmcnt(0)
	s_barrier
	s_mov_b64 s[2:3], exec
	v_readlane_b32 s12, v253, 36
	v_readlane_b32 s13, v253, 37
	s_and_b64 s[12:13], s[2:3], s[12:13]
	s_mov_b64 exec, s[12:13]
	s_cbranch_execz .LBB0_244
	s_cmp_lg_u32 s98, 0
	s_cbranch_scc0 .Lgb_full_244
	buffer_wbl2 sc1
	s_waitcnt vmcnt(0)
	v_readlane_b32 s4, v253, 1
	v_readlane_b32 s12, v253, 56
	v_readlane_b32 s13, v253, 57
	s_nop 3
	s_bfe_u32 s4, s4, 0x20001
	s_lshl_b32 s4, s4, 8
	s_add_i32 s4, s4, 0x7000
	v_mov_b32_e32 v2, s4
	s_add_i32 s16, s92, 1
	s_lshl_b32 s16, s16, 6
	s_mov_b32 s1, 0
	s_nop 1
	global_atomic_add v5, v2, v234, s[12:13] sc0
	s_waitcnt vmcnt(0)
	v_readfirstlane_b32 s4, v5
	s_nop 3
	s_add_i32 s4, s4, 1
	s_cmp_ge_u32 s4, s16
	s_cbranch_scc1 .Lgb_pair_ok_244
.Lgb_pair_244:
	global_load_dword v3, v2, s[12:13] sc1
	s_waitcnt vmcnt(0)
	v_readfirstlane_b32 s4, v3
	s_nop 3
	s_cmp_ge_u32 s4, s16
	s_cbranch_scc1 .Lgb_pair_ok_244
	s_sleep 1
	s_add_i32 s1, s1, 1
	s_cmp_lt_u32 s1, 0x40000
	s_cbranch_scc1 .Lgb_pair_244
